# cache policy: nt on the fp8 conversion's output stores (full 256B row pieces, read a phase or a layer later)
# speedup vs baseline: 1.0309x; 1.0084x over previous
; #define LAS __attribute__((address_space(3)))
; __device__ __forceinline__ void witem_store(const Frame& F, const WItem& t, const f32x4 (&v)[16], LAS unsigned char* tile) {
;     const int i = F.lane & 31, hi = F.lane >> 5;
; #pragma unroll
;     for (int j = 0; j < 4; ++j) {
;         u32x4 o;
; #pragma unroll
;         for (int d = 0; d < 4; ++d) { int r = __builtin_amdgcn_cvt_pk_fp8_f32(v[4 * d][j] * t.scale, v[4 * d + 1][j] * t.scale, 0, false);
;             r = __builtin_amdgcn_cvt_pk_fp8_f32(v[4 * d + 2][j] * t.scale, v[4 * d + 3][j] * t.scale, r, true); o[d] = (unsigned)r; }
;         *(LAS u32x4*)(tile + (32 * j + i) * 272 + 32 * F.wave + 16 * hi) = o;
;     }
;     __syncthreads();
.LBB0_1347:
	v_mul_f32_e32 v149, v147, v38
	v_mul_f32_e32 v150, v147, v42
	v_mov_b32_e32 v148, v199
	v_cvt_pk_fp8_f32 v148, v149, v150
	v_mul_f32_e32 v149, v147, v46
	v_mul_f32_e32 v150, v147, v54
	v_mul_f32_e32 v151, v147, v66
	v_cvt_pk_fp8_f32 v148, v149, v150 op_sel:[0,0,1]
	v_mul_f32_e32 v150, v147, v58
	v_mov_b32_e32 v149, v199
	v_cvt_pk_fp8_f32 v149, v150, v151
	v_mul_f32_e32 v150, v147, v74
	v_mul_f32_e32 v151, v147, v78
	v_mul_f32_e32 v152, v147, v98
	v_cvt_pk_fp8_f32 v149, v150, v151 op_sel:[0,0,1]
	v_mul_f32_e32 v151, v147, v90
	v_mov_b32_e32 v150, v199
	v_cvt_pk_fp8_f32 v150, v151, v152
	v_mul_f32_e32 v151, v147, v106
	v_mul_f32_e32 v152, v147, v110
	v_mul_f32_e32 v153, v147, v118
	v_cvt_pk_fp8_f32 v150, v151, v152 op_sel:[0,0,1]
	v_mul_f32_e32 v152, v147, v114
	v_mov_b32_e32 v151, v199
	v_cvt_pk_fp8_f32 v151, v152, v153
	v_mul_f32_e32 v152, v147, v122
	v_mul_f32_e32 v153, v147, v126
	s_movk_i32 s7, 0xff80
	v_cvt_pk_fp8_f32 v151, v152, v153 op_sel:[0,0,1]
	v_mul_f32_e32 v152, v147, v99
	v_mul_f32_e32 v153, v147, v119
	s_ashr_i32 s37, s36, 31
	ds_write_b128 v141, v[148:151] offset:34816
	v_mul_f32_e32 v149, v147, v39
	v_mul_f32_e32 v150, v147, v43
	v_mov_b32_e32 v148, v199
	v_cvt_pk_fp8_f32 v148, v149, v150
	v_mul_f32_e32 v149, v147, v47
	v_mul_f32_e32 v150, v147, v55
	v_mul_f32_e32 v151, v147, v67
	v_cvt_pk_fp8_f32 v148, v149, v150 op_sel:[0,0,1]
	v_mul_f32_e32 v150, v147, v59
	v_mov_b32_e32 v149, v199
	v_cvt_pk_fp8_f32 v149, v150, v151
	v_mul_f32_e32 v150, v147, v75
	v_mul_f32_e32 v151, v147, v79
	v_cvt_pk_fp8_f32 v149, v150, v151 op_sel:[0,0,1]
	v_mul_f32_e32 v151, v147, v91
	v_mov_b32_e32 v150, v199
	v_cvt_pk_fp8_f32 v150, v151, v152
	v_mul_f32_e32 v151, v147, v107
	v_mul_f32_e32 v152, v147, v111
	v_cvt_pk_fp8_f32 v150, v151, v152 op_sel:[0,0,1]
	v_mul_f32_e32 v152, v147, v115
	v_mov_b32_e32 v151, v199
	v_cvt_pk_fp8_f32 v151, v152, v153
	v_mul_f32_e32 v152, v147, v123
	v_mul_f32_e32 v153, v147, v127
	v_cvt_pk_fp8_f32 v151, v152, v153 op_sel:[0,0,1]
	v_mul_f32_e32 v152, v147, v100
	v_mul_f32_e32 v153, v147, v120
	ds_write_b128 v141, v[148:151] offset:43520
	v_mul_f32_e32 v149, v147, v40
	v_mul_f32_e32 v150, v147, v44
	v_mov_b32_e32 v148, v199
	v_cvt_pk_fp8_f32 v148, v149, v150
	v_mul_f32_e32 v149, v147, v48
	v_mul_f32_e32 v150, v147, v56
	v_mul_f32_e32 v151, v147, v68
	v_cvt_pk_fp8_f32 v148, v149, v150 op_sel:[0,0,1]
	v_mul_f32_e32 v150, v147, v60
	v_mov_b32_e32 v149, v199
	v_cvt_pk_fp8_f32 v149, v150, v151
	v_mul_f32_e32 v150, v147, v76
	v_mul_f32_e32 v151, v147, v80
	v_cvt_pk_fp8_f32 v149, v150, v151 op_sel:[0,0,1]
	v_mul_f32_e32 v151, v147, v92
	v_mov_b32_e32 v150, v199
	v_cvt_pk_fp8_f32 v150, v151, v152
	v_mul_f32_e32 v151, v147, v108
	v_mul_f32_e32 v152, v147, v112
	v_cvt_pk_fp8_f32 v150, v151, v152 op_sel:[0,0,1]
	v_mul_f32_e32 v152, v147, v116
	v_mov_b32_e32 v151, v199
	v_cvt_pk_fp8_f32 v151, v152, v153
	v_mul_f32_e32 v152, v147, v124
	v_mul_f32_e32 v153, v147, v128
	v_cvt_pk_fp8_f32 v151, v152, v153 op_sel:[0,0,1]
	v_mul_f32_e32 v152, v147, v101
	v_mul_f32_e32 v153, v147, v121
	ds_write_b128 v141, v[148:151] offset:52224
	v_mul_f32_e32 v149, v147, v41
	v_mul_f32_e32 v150, v147, v45
	v_mov_b32_e32 v148, v199
	v_cvt_pk_fp8_f32 v148, v149, v150
	v_mul_f32_e32 v149, v147, v49
	v_mul_f32_e32 v150, v147, v57
	v_mul_f32_e32 v151, v147, v69
	v_cvt_pk_fp8_f32 v148, v149, v150 op_sel:[0,0,1]
	v_mul_f32_e32 v150, v147, v61
	v_mov_b32_e32 v149, v199
	v_cvt_pk_fp8_f32 v149, v150, v151
	v_mul_f32_e32 v150, v147, v77
	v_mul_f32_e32 v151, v147, v81
	v_cvt_pk_fp8_f32 v149, v150, v151 op_sel:[0,0,1]
	v_mul_f32_e32 v151, v147, v93
	v_mov_b32_e32 v150, v199
	v_cvt_pk_fp8_f32 v150, v151, v152
	v_mul_f32_e32 v151, v147, v109
	v_mul_f32_e32 v152, v147, v113
	v_cvt_pk_fp8_f32 v150, v151, v152 op_sel:[0,0,1]
	v_mul_f32_e32 v152, v147, v117
	v_mov_b32_e32 v151, v199
	v_cvt_pk_fp8_f32 v151, v152, v153
	v_mul_f32_e32 v152, v147, v125
	v_mul_f32_e32 v153, v147, v129
	v_cvt_pk_fp8_f32 v151, v152, v153 op_sel:[0,0,1]
	v_add_u32_e32 v152, s40, v131
	v_ashrrev_i32_e32 v153, 3, v152
	v_and_b32_e32 v154, 0x63, v152
	v_and_or_b32 v153, v153, s7, v154
	v_lshlrev_b32_e32 v154, 1, v152
	v_and_b32_e32 v154, 0x700, v154
	v_add_u32_e32 v153, v153, v154
	v_lshrrev_b32_e32 v154, 1, v152
	v_lshlrev_b32_e32 v152, 2, v152
	v_and_b32_e32 v154, 12, v154
	v_and_b32_e32 v152, 16, v152
	v_or3_b32 v152, v153, v154, v152
	ds_write_b128 v141, v[148:151] offset:60928
	s_waitcnt lgkmcnt(0)
	s_barrier
; #define LAS __attribute__((address_space(3)))
; __device__ __forceinline__ int map_row_rt(int map, int n) { return map == 0 ? n : (map == 1 ? map_row<1>(n) : (map == 3 ? map_row<3>(n) : map_row<2>(n))); }
; __device__ __forceinline__ void witem_store(const Frame& F, const WItem& t, const f32x4 (&v)[16], LAS unsigned char* tile) {
;     ...
;     const int c = F.tid & 15;
; #pragma unroll
;     for (int pass = 0; pass < 4; ++pass) { const int n = (F.tid >> 4) + 32 * pass, rho = (n & 3) * 32 + (n >> 2);
;         const u32x4 o = *(const LAS u32x4*)(tile + rho * 272 + 16 * c);
;         *(u32x4*)(t.WT + (size_t)map_row_rt(t.map, t.n0 + n) * D + t.k0 + 16 * c) = o; }
	ds_read_b128 v[148:151], v142 offset:34816
	v_ashrrev_i32_e32 v153, 31, v152
	v_lshlrev_b64 v[152:153], 10, v[152:153]
	v_lshl_add_u64 v[152:153], s[28:29], 0, v[152:153]
	v_lshl_add_u64 v[152:153], v[152:153], 0, s[36:37]
	v_lshl_add_u64 v[152:153], v[152:153], 0, v[132:133]
	s_waitcnt lgkmcnt(0)
	global_store_dwordx4 v[152:153], v[148:151], off nt
	v_add_u32_e32 v152, s40, v134
	v_ashrrev_i32_e32 v153, 3, v152
	v_and_b32_e32 v154, 0x63, v152
	v_and_or_b32 v153, v153, s7, v154
	v_lshlrev_b32_e32 v154, 1, v152
	v_and_b32_e32 v154, 0x700, v154
	v_add_u32_e32 v153, v153, v154
	v_lshrrev_b32_e32 v154, 1, v152
	v_lshlrev_b32_e32 v152, 2, v152
	v_and_b32_e32 v154, 12, v154
	v_and_b32_e32 v152, 16, v152
	v_or3_b32 v152, v153, v154, v152
	ds_read_b128 v[148:151], v143 offset:34816
	v_ashrrev_i32_e32 v153, 31, v152
	v_lshlrev_b64 v[152:153], 10, v[152:153]
	v_lshl_add_u64 v[152:153], s[28:29], 0, v[152:153]
	v_lshl_add_u64 v[152:153], v[152:153], 0, s[36:37]
	v_lshl_add_u64 v[152:153], v[152:153], 0, v[132:133]
	s_waitcnt lgkmcnt(0)
	global_store_dwordx4 v[152:153], v[148:151], off nt
	v_add_u32_e32 v152, s40, v135
	v_ashrrev_i32_e32 v153, 3, v152
	v_and_b32_e32 v154, 0x63, v152
	v_and_or_b32 v153, v153, s7, v154
	v_lshlrev_b32_e32 v154, 1, v152
	v_and_b32_e32 v154, 0x700, v154
	v_add_u32_e32 v153, v153, v154
	v_lshrrev_b32_e32 v154, 1, v152
	v_lshlrev_b32_e32 v152, 2, v152
	v_and_b32_e32 v154, 12, v154
	v_and_b32_e32 v152, 16, v152
	v_or3_b32 v152, v153, v154, v152
	ds_read_b128 v[148:151], v144 offset:34816
	v_ashrrev_i32_e32 v153, 31, v152
	v_lshlrev_b64 v[152:153], 10, v[152:153]
	v_lshl_add_u64 v[152:153], s[28:29], 0, v[152:153]
	v_lshl_add_u64 v[152:153], v[152:153], 0, s[36:37]
	v_lshl_add_u64 v[152:153], v[152:153], 0, v[132:133]
	s_waitcnt lgkmcnt(0)
	global_store_dwordx4 v[152:153], v[148:151], off nt
	v_add_u32_e32 v152, s40, v136
	v_ashrrev_i32_e32 v153, 3, v152
	v_and_b32_e32 v154, 0x63, v152
	v_and_or_b32 v153, v153, s7, v154
	v_lshlrev_b32_e32 v154, 1, v152
	v_and_b32_e32 v154, 0x700, v154
	v_add_u32_e32 v153, v153, v154
	v_lshrrev_b32_e32 v154, 1, v152
	v_lshlrev_b32_e32 v152, 2, v152
	v_and_b32_e32 v154, 12, v154
	v_and_b32_e32 v152, 16, v152
	v_or3_b32 v152, v153, v154, v152
	ds_read_b128 v[148:151], v145 offset:34816
	v_ashrrev_i32_e32 v153, 31, v152
	v_lshlrev_b64 v[152:153], 10, v[152:153]
	v_lshl_add_u64 v[152:153], s[28:29], 0, v[152:153]
	v_lshl_add_u64 v[152:153], v[152:153], 0, s[36:37]
	v_lshl_add_u64 v[152:153], v[152:153], 0, v[132:133]
	s_waitcnt lgkmcnt(0)
	global_store_dwordx4 v[152:153], v[148:151], off nt
	s_and_b64 vcc, exec, s[26:27]
	s_cbranch_vccnz .LBB0_1354

; #define LAS __attribute__((address_space(3)))
; __device__ __forceinline__ int map_row_rt(int map, int n) { return map == 0 ? n : (map == 1 ? map_row<1>(n) : (map == 3 ? map_row<3>(n) : map_row<2>(n))); }
; __device__ __forceinline__ void witem_store(const Frame& F, const WItem& t, const f32x4 (&v)[16], LAS unsigned char* tile) {
;     const int i = F.lane & 31, hi = F.lane >> 5;
; #pragma unroll
;     for (int j = 0; j < 4; ++j) {
;         u32x4 o;
; #pragma unroll
;         for (int d = 0; d < 4; ++d) { int r = __builtin_amdgcn_cvt_pk_fp8_f32(v[4 * d][j] * t.scale, v[4 * d + 1][j] * t.scale, 0, false);
;             r = __builtin_amdgcn_cvt_pk_fp8_f32(v[4 * d + 2][j] * t.scale, v[4 * d + 3][j] * t.scale, r, true); o[d] = (unsigned)r; }
;         *(LAS u32x4*)(tile + (32 * j + i) * 272 + 32 * F.wave + 16 * hi) = o;
;     }
;     __syncthreads();
;     const int c = F.tid & 15;
; #pragma unroll
;     for (int pass = 0; pass < 4; ++pass) { const int n = (F.tid >> 4) + 32 * pass, rho = (n & 3) * 32 + (n >> 2);
;         const u32x4 o = *(const LAS u32x4*)(tile + rho * 272 + 16 * c);
;         *(u32x4*)(t.WT + (size_t)map_row_rt(t.map, t.n0 + n) * D + t.k0 + 16 * c) = o; }
.LBB0_1350:
	s_waitcnt vmcnt(15)
	v_mul_f32_e32 v149, v2, v146
	s_waitcnt vmcnt(14)
	v_mul_f32_e32 v150, v6, v146
	v_mov_b32_e32 v148, v199
	v_cvt_pk_fp8_f32 v148, v149, v150
	s_waitcnt vmcnt(13)
	v_mul_f32_e32 v149, v10, v146
	s_waitcnt vmcnt(12)
	v_mul_f32_e32 v150, v14, v146
	s_waitcnt vmcnt(10)
	v_mul_f32_e32 v151, v22, v146
	v_cvt_pk_fp8_f32 v148, v149, v150 op_sel:[0,0,1]
	v_mul_f32_e32 v150, v18, v146
	v_mov_b32_e32 v149, v199
	v_cvt_pk_fp8_f32 v149, v150, v151
	s_waitcnt vmcnt(9)
	v_mul_f32_e32 v150, v26, v146
	s_waitcnt vmcnt(8)
	v_mul_f32_e32 v151, v30, v146
	s_waitcnt vmcnt(6)
	v_mul_f32_e32 v152, v50, v146
	v_cvt_pk_fp8_f32 v149, v150, v151 op_sel:[0,0,1]
	v_mul_f32_e32 v151, v34, v146
	v_mov_b32_e32 v150, v199
	v_cvt_pk_fp8_f32 v150, v151, v152
	s_waitcnt vmcnt(5)
	v_mul_f32_e32 v151, v62, v146
	s_waitcnt vmcnt(4)
	v_mul_f32_e32 v152, v70, v146
	s_waitcnt vmcnt(2)
	v_mul_f32_e32 v153, v86, v146
	v_cvt_pk_fp8_f32 v150, v151, v152 op_sel:[0,0,1]
	v_mul_f32_e32 v152, v82, v146
	v_mov_b32_e32 v151, v199
	v_cvt_pk_fp8_f32 v151, v152, v153
	s_waitcnt vmcnt(1)
	v_mul_f32_e32 v152, v94, v146
	s_waitcnt vmcnt(0)
	v_mul_f32_e32 v153, v146, v102
	s_movk_i32 s7, 0xff80
	v_cvt_pk_fp8_f32 v151, v152, v153 op_sel:[0,0,1]
	v_mul_f32_e32 v152, v51, v146
	v_mul_f32_e32 v153, v87, v146
	s_ashr_i32 s43, s42, 31
	ds_write_b128 v141, v[148:151]
	v_mul_f32_e32 v149, v3, v146
	v_mul_f32_e32 v150, v7, v146
	v_mov_b32_e32 v148, v199
	v_cvt_pk_fp8_f32 v148, v149, v150
	v_mul_f32_e32 v149, v11, v146
	v_mul_f32_e32 v150, v15, v146
	v_mul_f32_e32 v151, v23, v146
	v_cvt_pk_fp8_f32 v148, v149, v150 op_sel:[0,0,1]
	v_mul_f32_e32 v150, v19, v146
	v_mov_b32_e32 v149, v199
	v_cvt_pk_fp8_f32 v149, v150, v151
	v_mul_f32_e32 v150, v27, v146
	v_mul_f32_e32 v151, v31, v146
	s_andn2_b64 vcc, exec, s[26:27]
	v_cvt_pk_fp8_f32 v149, v150, v151 op_sel:[0,0,1]
	v_mul_f32_e32 v151, v35, v146
	v_mov_b32_e32 v150, v199
	v_cvt_pk_fp8_f32 v150, v151, v152
	v_mul_f32_e32 v151, v63, v146
	v_mul_f32_e32 v152, v71, v146
	v_cvt_pk_fp8_f32 v150, v151, v152 op_sel:[0,0,1]
	v_mul_f32_e32 v152, v83, v146
	v_mov_b32_e32 v151, v199
	v_cvt_pk_fp8_f32 v151, v152, v153
	v_mul_f32_e32 v152, v95, v146
	v_mul_f32_e32 v153, v146, v103
	v_cvt_pk_fp8_f32 v151, v152, v153 op_sel:[0,0,1]
	v_mul_f32_e32 v152, v52, v146
	v_mul_f32_e32 v153, v88, v146
	ds_write_b128 v141, v[148:151] offset:8704
	v_mul_f32_e32 v149, v4, v146
	v_mul_f32_e32 v150, v8, v146
	v_mov_b32_e32 v148, v199
	v_cvt_pk_fp8_f32 v148, v149, v150
	v_mul_f32_e32 v149, v12, v146
	v_mul_f32_e32 v150, v16, v146
	v_mul_f32_e32 v151, v24, v146
	v_cvt_pk_fp8_f32 v148, v149, v150 op_sel:[0,0,1]
	v_mul_f32_e32 v150, v20, v146
	v_mov_b32_e32 v149, v199
	v_cvt_pk_fp8_f32 v149, v150, v151
	v_mul_f32_e32 v150, v28, v146
	v_mul_f32_e32 v151, v32, v146
	v_cvt_pk_fp8_f32 v149, v150, v151 op_sel:[0,0,1]
	v_mul_f32_e32 v151, v36, v146
	v_mov_b32_e32 v150, v199
	v_cvt_pk_fp8_f32 v150, v151, v152
	v_mul_f32_e32 v151, v64, v146
	v_mul_f32_e32 v152, v72, v146
	v_cvt_pk_fp8_f32 v150, v151, v152 op_sel:[0,0,1]
	v_mul_f32_e32 v152, v84, v146
	v_mov_b32_e32 v151, v199
	v_cvt_pk_fp8_f32 v151, v152, v153
	v_mul_f32_e32 v152, v96, v146
	v_mul_f32_e32 v153, v146, v104
	v_cvt_pk_fp8_f32 v151, v152, v153 op_sel:[0,0,1]
	v_mul_f32_e32 v152, v53, v146
	v_mul_f32_e32 v153, v89, v146
	ds_write_b128 v141, v[148:151] offset:17408
	v_mul_f32_e32 v149, v5, v146
	v_mul_f32_e32 v150, v9, v146
	v_mov_b32_e32 v148, v199
	v_cvt_pk_fp8_f32 v148, v149, v150
	v_mul_f32_e32 v149, v13, v146
	v_mul_f32_e32 v150, v17, v146
	v_mul_f32_e32 v151, v25, v146
	v_cvt_pk_fp8_f32 v148, v149, v150 op_sel:[0,0,1]
	v_mul_f32_e32 v150, v21, v146
	v_mov_b32_e32 v149, v199
	v_cvt_pk_fp8_f32 v149, v150, v151
	v_mul_f32_e32 v150, v29, v146
	v_mul_f32_e32 v151, v33, v146
	v_cvt_pk_fp8_f32 v149, v150, v151 op_sel:[0,0,1]
	v_mul_f32_e32 v151, v37, v146
	v_mov_b32_e32 v150, v199
	v_cvt_pk_fp8_f32 v150, v151, v152
	v_mul_f32_e32 v151, v65, v146
	v_mul_f32_e32 v152, v73, v146
	v_cvt_pk_fp8_f32 v150, v151, v152 op_sel:[0,0,1]
	v_mul_f32_e32 v152, v85, v146
	v_mov_b32_e32 v151, v199
	v_cvt_pk_fp8_f32 v151, v152, v153
	v_mul_f32_e32 v152, v97, v146
	v_mul_f32_e32 v153, v146, v105
	v_cvt_pk_fp8_f32 v151, v152, v153 op_sel:[0,0,1]
	v_add_u32_e32 v152, s44, v131
	v_lshlrev_b32_e32 v153, 1, v152
	v_ashrrev_i32_e32 v152, 3, v152
	v_and_b32_e32 v153, 0x700, v153
	v_and_or_b32 v152, v152, s7, v137
	v_add_u32_e32 v152, v152, v153
	ds_write_b128 v141, v[148:151] offset:26112
	s_waitcnt lgkmcnt(0)
	s_barrier
	ds_read_b128 v[148:151], v142
	v_ashrrev_i32_e32 v153, 31, v152
	v_lshlrev_b64 v[152:153], 10, v[152:153]
	v_lshl_add_u64 v[152:153], s[14:15], 0, v[152:153]
	v_lshl_add_u64 v[152:153], v[152:153], 0, s[42:43]
	v_lshl_add_u64 v[152:153], v[152:153], 0, v[132:133]
	s_waitcnt lgkmcnt(0)
	global_store_dwordx4 v[152:153], v[148:151], off nt
	v_add_u32_e32 v152, s44, v134
	v_lshlrev_b32_e32 v153, 1, v152
	v_ashrrev_i32_e32 v152, 3, v152
	v_and_b32_e32 v153, 0x700, v153
	v_and_or_b32 v152, v152, s7, v138
	v_add_u32_e32 v152, v152, v153
	ds_read_b128 v[148:151], v143
	v_ashrrev_i32_e32 v153, 31, v152
	v_lshlrev_b64 v[152:153], 10, v[152:153]
	v_lshl_add_u64 v[152:153], s[14:15], 0, v[152:153]
	v_lshl_add_u64 v[152:153], v[152:153], 0, s[42:43]
	v_lshl_add_u64 v[152:153], v[152:153], 0, v[132:133]
	s_waitcnt lgkmcnt(0)
	global_store_dwordx4 v[152:153], v[148:151], off nt
	v_add_u32_e32 v152, s44, v135
	v_lshlrev_b32_e32 v153, 1, v152
	v_ashrrev_i32_e32 v152, 3, v152
	v_and_b32_e32 v153, 0x700, v153
	v_and_or_b32 v152, v152, s7, v139
	v_add_u32_e32 v152, v152, v153
	ds_read_b128 v[148:151], v144
	v_ashrrev_i32_e32 v153, 31, v152
	v_lshlrev_b64 v[152:153], 10, v[152:153]
	v_lshl_add_u64 v[152:153], s[14:15], 0, v[152:153]
	v_lshl_add_u64 v[152:153], v[152:153], 0, s[42:43]
	v_lshl_add_u64 v[152:153], v[152:153], 0, v[132:133]
	s_waitcnt lgkmcnt(0)
	global_store_dwordx4 v[152:153], v[148:151], off nt
	v_add_u32_e32 v152, s44, v136
	v_lshlrev_b32_e32 v153, 1, v152
	v_ashrrev_i32_e32 v152, 3, v152
	v_and_b32_e32 v153, 0x700, v153
	v_and_or_b32 v152, v152, s7, v140
	v_add_u32_e32 v152, v152, v153
	ds_read_b128 v[148:151], v145
	v_ashrrev_i32_e32 v153, 31, v152
	v_lshlrev_b64 v[152:153], 10, v[152:153]
	v_lshl_add_u64 v[152:153], s[14:15], 0, v[152:153]
	v_lshl_add_u64 v[152:153], v[152:153], 0, s[42:43]
	v_lshl_add_u64 v[152:153], v[152:153], 0, v[132:133]
	s_waitcnt lgkmcnt(0)
	global_store_dwordx4 v[152:153], v[148:151], off nt
	s_cbranch_vccnz .LBB0_1353
; __device__ __forceinline__ float w_qscale(float wmax) { return exp2f(floorf(log2f(128.f / fmaxf(wmax, 1e-30f)))); }
; __device__ __forceinline__ bool witem_decode(const Frame& F, int l, int it, WItem& t) {
;     constexpr int I_GU = 4 * 16, I_DN = 4 * 8, N_GU = NE * I_GU, N_DN = NE * I_DN;
;     const float* wmax = (const float*)((const unsigned*)(F.ws + WS_CTL) + CW_WMAX);
;     int r = it, nblk, item;
;     if (r < N_GU) { const int le = l * NE + r / I_GU; t.W = F.in[16] + (size_t)le * D * 2048; t.WT = (unsigned char*)(F.ws + WS_WGU) + (size_t)le * 2048 * D; t.N = 2048; t.map = 1; nblk = 16; item = r % I_GU; t.scale = w_qscale(wmax[l * 2 + 0]); }
;     else if ((r -= N_GU) < N_DN) { const int le = l * NE + r / I_DN; t.W = F.in[18] + (size_t)le * FF * D; t.WT = (unsigned char*)(F.ws + WS_WDN) + (size_t)le * D * FF; t.N = D; t.map = 3; nblk = 8; item = r % I_DN; t.scale = w_qscale(wmax[l * 2 + 1]); }
;     else return false;
;     t.k0 = 256 * (item / nblk); t.n0 = 128 * (item % nblk); return true;
; }
; __device__ __forceinline__ void witem_load(const WItem& t, int wave, int lane, f32x4 (&v)[16]) {
;     const float* wp = t.W + (size_t)(t.k0 + 32 * wave + 16 * (lane >> 5)) * t.N + t.n0 + 4 * (lane & 31);
; #pragma unroll
;     for (int q = 0; q < 16; ++q) v[q] = __builtin_nontemporal_load((const f32x4*)(wp + (size_t)q * t.N));
; }
; __device__ __forceinline__ void fp8_convert_range(const Frame& F, int l, int start, int stride, int limit) {
;     ...
;     while (ha) {
;         const bool hb = it + stride < limit && witem_decode(F, l, it + stride, tb);
;         if (hb) witem_load(tb, F.wave, F.lane, vb);
;         witem_store(F, ta, va, F.lds);
;         if (!hb) break;
;         it += 2 * stride;
;         ha = it < limit && witem_decode(F, l, it, ta);
;         if (ha) witem_load(ta, F.wave, F.lane, va);
	s_lshl_b32 s7, s74, 1
	s_add_i32 s6, s6, s7
	s_cmp_ge_i32 s6, s100
	s_cselect_b64 s[26:27], -1, 0
	s_and_b64 vcc, exec, s[26:27]
	s_cbranch_vccnz .LBB0_1347
	global_load_dword v2, v199, s[0:1]
	s_ashr_i32 s7, s6, 31
	s_lshr_b32 s7, s7, 26
	s_add_i32 s7, s6, s7
	s_ashr_i32 s8, s7, 6
	s_add_i32 s8, s8, s4
	s_ashr_i32 s9, s8, 31
	v_readlane_b32 s44, v249, 8
	s_lshl_b64 s[10:11], s[8:9], 23
	v_readlane_b32 s46, v249, 10
	v_readlane_b32 s47, v249, 11
	s_add_u32 s46, s46, s10
	s_addc_u32 s47, s47, s11
	s_lshl_b64 s[8:9], s[8:9], 21
	s_add_u32 s14, s3, s8
	s_mov_b32 s10, 0x43000000
	s_addc_u32 s15, s5, s9
	s_and_b32 s7, s7, 0xffc0
	s_sub_i32 s7, s6, s7
	v_readlane_b32 s45, v249, 9
	v_lshlrev_b32_e32 v198, 2, v130
	v_readlane_b32 s48, v249, 12
	v_readlane_b32 s49, v249, 13
	v_readlane_b32 s50, v249, 14
	v_readlane_b32 s51, v249, 15
	s_waitcnt vmcnt(0)
	v_max_f32_e32 v2, v2, v2
	v_max_f32_e32 v2, 0xda24260, v2
	v_div_scale_f32 v3, s[8:9], v2, v2, s10
	v_rcp_f32_e32 v4, v3
	s_mov_b32 s8, 0x800000
	v_fma_f32 v5, -v3, v4, 1.0
	v_fmac_f32_e32 v4, v5, v4
	v_div_scale_f32 v5, vcc, s10, v2, s10
	v_mul_f32_e32 v6, v5, v4
	v_fma_f32 v7, -v3, v6, v5
	v_fmac_f32_e32 v6, v7, v4
	v_fma_f32 v3, -v3, v6, v5
	v_div_fmas_f32 v3, v3, v4, v6
	v_div_fixup_f32 v2, v3, v2, s10
	v_cmp_gt_f32_e32 vcc, s8, v2
	s_and_b64 s[8:9], vcc, exec
	s_cselect_b32 s8, 32, 0
	v_ldexp_f32 v2, v2, s8
	v_log_f32_e32 v2, v2
	v_cndmask_b32_e32 v3, 0, v232, vcc
	s_mov_b32 s8, 0xc2fc0000
	v_sub_f32_e32 v2, v2, v3
	v_floor_f32_e32 v2, v2
	v_cmp_gt_f32_e32 vcc, s8, v2
	s_and_b64 s[8:9], vcc, exec
	s_cselect_b32 s8, 0xffffffc0, 0
	v_cndmask_b32_e32 v3, 0, v233, vcc
	v_add_f32_e32 v2, v2, v3
	v_exp_f32_e32 v2, v2
	s_nop 0
	v_ldexp_f32 v146, v2, s8
	s_bfe_i32 s8, s7, 0x80000
	s_bfe_u32 s8, s8, 0x4000b
	s_add_i32 s8, s7, s8
	s_bfe_i32 s9, s8, 0x80000
	s_sext_i32_i16 s9, s9
	s_lshl_b32 s9, s9, 4
	s_and_b32 s42, s9, 0xffffff00
	s_and_b32 s8, s8, 0xf0
	s_sub_i32 s7, s7, s8
	v_add_u32_e32 v2, s42, v1
	s_sext_i32_i8 s7, s7
	v_ashrrev_i32_e32 v3, 31, v2
	s_lshl_b32 s44, s7, 7
	v_lshlrev_b64 v[2:3], 13, v[2:3]
	v_lshl_add_u64 v[2:3], s[46:47], 0, v[2:3]
	s_ashr_i32 s45, s44, 31
	v_lshl_add_u64 v[2:3], s[44:45], 2, v[2:3]
	v_lshl_add_u64 v[102:103], v[2:3], 0, v[198:199]
	v_add_co_u32_e32 v6, vcc, s70, v102
	s_movk_i32 s7, 0x4000
	s_nop 0
	v_addc_co_u32_e32 v7, vcc, 0, v103, vcc
	v_add_co_u32_e32 v10, vcc, s7, v102
	s_movk_i32 s7, 0x6000
	s_nop 0
	v_addc_co_u32_e32 v11, vcc, 0, v103, vcc
	v_add_co_u32_e32 v14, vcc, s7, v102
	s_mov_b32 s7, 0x8000
	s_nop 0
	v_addc_co_u32_e32 v15, vcc, 0, v103, vcc
	v_add_co_u32_e32 v18, vcc, s7, v102
	s_mov_b32 s7, 0xa000
	s_nop 0
	v_addc_co_u32_e32 v19, vcc, 0, v103, vcc
	v_add_co_u32_e32 v22, vcc, s7, v102
	s_mov_b32 s7, 0xc000
	s_nop 0
	v_addc_co_u32_e32 v23, vcc, 0, v103, vcc
	v_add_co_u32_e32 v26, vcc, s7, v102
	s_mov_b32 s7, 0xe000
	s_nop 0
	v_addc_co_u32_e32 v27, vcc, 0, v103, vcc
	v_add_co_u32_e32 v30, vcc, s7, v102
	s_mov_b32 s7, 0x12000
	s_nop 0
	v_addc_co_u32_e32 v31, vcc, 0, v103, vcc
	v_add_co_u32_e32 v34, vcc, s71, v102
	global_load_dwordx4 v[2:5], v[102:103], off nt
	s_nop 0
	v_addc_co_u32_e32 v35, vcc, 0, v103, vcc
	v_add_co_u32_e32 v50, vcc, s7, v102
	s_mov_b32 s7, 0x14000
	s_nop 0
	v_addc_co_u32_e32 v51, vcc, 0, v103, vcc
	v_add_co_u32_e32 v62, vcc, s7, v102
	s_mov_b32 s7, 0x16000
	s_nop 0
	v_addc_co_u32_e32 v63, vcc, 0, v103, vcc
	v_add_co_u32_e32 v70, vcc, s7, v102
	s_mov_b32 s7, 0x18000
	s_nop 0
	v_addc_co_u32_e32 v71, vcc, 0, v103, vcc
	v_add_co_u32_e32 v82, vcc, s7, v102
	global_load_dwordx4 v[6:9], v[6:7], off nt
	s_nop 0
	v_addc_co_u32_e32 v83, vcc, 0, v103, vcc
	v_add_co_u32_e32 v86, vcc, 0x1a000, v102
	global_load_dwordx4 v[10:13], v[10:11], off nt
	s_nop 0
	v_addc_co_u32_e32 v87, vcc, 0, v103, vcc
	v_add_co_u32_e32 v94, vcc, 0x1c000, v102
	global_load_dwordx4 v[14:17], v[14:15], off nt
	s_nop 0
	v_addc_co_u32_e32 v95, vcc, 0, v103, vcc
	v_add_co_u32_e32 v102, vcc, 0x1e000, v102
	global_load_dwordx4 v[18:21], v[18:19], off nt
	s_nop 0
	v_addc_co_u32_e32 v103, vcc, 0, v103, vcc
	global_load_dwordx4 v[22:25], v[22:23], off nt
	s_nop 0
	global_load_dwordx4 v[26:29], v[26:27], off nt
	s_nop 0
	global_load_dwordx4 v[30:33], v[30:31], off nt
	s_nop 0
	global_load_dwordx4 v[34:37], v[34:35], off nt
	s_nop 0
	global_load_dwordx4 v[50:53], v[50:51], off nt
	s_nop 0
	global_load_dwordx4 v[62:65], v[62:63], off nt
	s_nop 0
	global_load_dwordx4 v[70:73], v[70:71], off nt
	s_nop 0
	global_load_dwordx4 v[82:85], v[82:83], off nt
	s_nop 0
	global_load_dwordx4 v[86:89], v[86:87], off nt
	s_nop 0
	global_load_dwordx4 v[94:97], v[94:95], off nt
	s_nop 0
	global_load_dwordx4 v[102:105], v[102:103], off nt
	s_branch .LBB0_1347

; #define LAS __attribute__((address_space(3)))
; __device__ __forceinline__ int map_row_rt(int map, int n) { return map == 0 ? n : (map == 1 ? map_row<1>(n) : (map == 3 ? map_row<3>(n) : map_row<2>(n))); }
; __device__ __forceinline__ void witem_store(const Frame& F, const WItem& t, const f32x4 (&v)[16], LAS unsigned char* tile) {
;     ...
;     for (int pass = 0; pass < 4; ++pass) { const int n = (F.tid >> 4) + 32 * pass, rho = (n & 3) * 32 + (n >> 2);
;         const u32x4 o = *(const LAS u32x4*)(tile + rho * 272 + 16 * c);
;         *(u32x4*)(t.WT + (size_t)map_row_rt(t.map, t.n0 + n) * D + t.k0 + 16 * c) = o; }
.LBB0_1420:
	v_ashrrev_i32_e32 v139, 31, v138
	v_lshlrev_b64 v[138:139], 10, v[138:139]
	v_lshl_add_u64 v[138:139], s[42:43], 0, v[138:139]
	v_lshl_add_u64 v[138:139], v[138:139], 0, s[44:45]
	v_lshl_add_u64 v[138:139], v[138:139], 0, v[134:135]
	s_waitcnt lgkmcnt(0)
	global_store_dwordx4 v[138:139], v[130:133], off nt
	s_and_b64 vcc, exec, s[48:49]
	s_cbranch_vccnz .LBB0_1556

; #define LAS __attribute__((address_space(3)))
; __device__ __forceinline__ int map_row_rt(int map, int n) { return map == 0 ? n : (map == 1 ? map_row<1>(n) : (map == 3 ? map_row<3>(n) : map_row<2>(n))); }
; __device__ __forceinline__ void witem_store(const Frame& F, const WItem& t, const f32x4 (&v)[16], LAS unsigned char* tile) {
;     ...
;     for (int pass = 0; pass < 4; ++pass) { const int n = (F.tid >> 4) + 32 * pass, rho = (n & 3) * 32 + (n >> 2);
;         const u32x4 o = *(const LAS u32x4*)(tile + rho * 272 + 16 * c);
;         *(u32x4*)(t.WT + (size_t)map_row_rt(t.map, t.n0 + n) * D + t.k0 + 16 * c) = o; }
.LBB0_1443:
	v_ashrrev_i32_e32 v139, 31, v138
	v_lshlrev_b64 v[138:139], 10, v[138:139]
	v_lshl_add_u64 v[138:139], s[0:1], 0, v[138:139]
	s_ashr_i32 s15, s14, 31
	v_lshl_add_u64 v[138:139], v[138:139], 0, s[14:15]
	v_lshl_add_u64 v[138:139], v[138:139], 0, v[134:135]
	s_waitcnt lgkmcnt(0)
	global_store_dwordx4 v[138:139], v[130:133], off nt
	ds_read_b128 v[130:133], v146
	s_cmp_lt_i32 s8, 1
	v_add_u32_e32 v139, s28, v140
	s_cbranch_scc1 .LBB0_1448
	s_cmp_gt_i32 s8, 2
	s_cbranch_scc0 .LBB0_1449
	s_cmp_eq_u32 s8, 3
	s_mov_b64 s[4:5], -1
	s_cbranch_scc0 .LBB0_1447
	v_lshlrev_b32_e32 v138, 2, v139
	v_lshrrev_b32_e32 v150, 1, v139
	v_and_b32_e32 v138, 16, v138
	v_and_b32_e32 v150, 12, v150
	v_and_b32_e32 v151, 0xffffffe3, v139
	v_or3_b32 v138, v138, v151, v150
	s_mov_b64 s[4:5], 0

; #define LAS __attribute__((address_space(3)))
; __device__ __forceinline__ int map_row_rt(int map, int n) { return map == 0 ? n : (map == 1 ? map_row<1>(n) : (map == 3 ? map_row<3>(n) : map_row<2>(n))); }
; __device__ __forceinline__ void witem_store(const Frame& F, const WItem& t, const f32x4 (&v)[16], LAS unsigned char* tile) {
;     ...
;     for (int pass = 0; pass < 4; ++pass) { const int n = (F.tid >> 4) + 32 * pass, rho = (n & 3) * 32 + (n >> 2);
;         const u32x4 o = *(const LAS u32x4*)(tile + rho * 272 + 16 * c);
;         *(u32x4*)(t.WT + (size_t)map_row_rt(t.map, t.n0 + n) * D + t.k0 + 16 * c) = o; }
.LBB0_1458:
	v_ashrrev_i32_e32 v139, 31, v138
	v_lshlrev_b64 v[138:139], 10, v[138:139]
	v_lshl_add_u64 v[138:139], s[0:1], 0, v[138:139]
	v_lshl_add_u64 v[138:139], v[138:139], 0, s[14:15]
	v_lshl_add_u64 v[138:139], v[138:139], 0, v[134:135]
	s_waitcnt lgkmcnt(0)
	global_store_dwordx4 v[138:139], v[130:133], off nt
	ds_read_b128 v[130:133], v147
	s_cmp_lt_i32 s8, 1
	v_add_u32_e32 v139, s28, v141
	s_cbranch_scc1 .LBB0_1463
	s_cmp_gt_i32 s8, 2
	s_cbranch_scc0 .LBB0_1464
	s_cmp_eq_u32 s8, 3
	s_mov_b64 s[4:5], -1
	s_cbranch_scc0 .LBB0_1462
	v_lshlrev_b32_e32 v138, 2, v139
	v_lshrrev_b32_e32 v150, 1, v139
	v_and_b32_e32 v138, 16, v138
	v_and_b32_e32 v150, 12, v150
	v_and_b32_e32 v151, 0xffffffe3, v139
	v_or3_b32 v138, v138, v151, v150
	s_mov_b64 s[4:5], 0

; #define LAS __attribute__((address_space(3)))
; __device__ __forceinline__ int map_row_rt(int map, int n) { return map == 0 ? n : (map == 1 ? map_row<1>(n) : (map == 3 ? map_row<3>(n) : map_row<2>(n))); }
; __device__ __forceinline__ void witem_store(const Frame& F, const WItem& t, const f32x4 (&v)[16], LAS unsigned char* tile) {
;     ...
;     for (int pass = 0; pass < 4; ++pass) { const int n = (F.tid >> 4) + 32 * pass, rho = (n & 3) * 32 + (n >> 2);
;         const u32x4 o = *(const LAS u32x4*)(tile + rho * 272 + 16 * c);
;         *(u32x4*)(t.WT + (size_t)map_row_rt(t.map, t.n0 + n) * D + t.k0 + 16 * c) = o; }
.LBB0_1473:
	v_ashrrev_i32_e32 v139, 31, v138
	v_lshlrev_b64 v[138:139], 10, v[138:139]
	v_lshl_add_u64 v[138:139], s[0:1], 0, v[138:139]
	v_lshl_add_u64 v[138:139], v[138:139], 0, s[14:15]
	v_lshl_add_u64 v[138:139], v[138:139], 0, v[134:135]
	s_waitcnt lgkmcnt(0)
	global_store_dwordx4 v[138:139], v[130:133], off nt
	ds_read_b128 v[130:133], v148
	s_cmp_lt_i32 s8, 1
	v_add_u32_e32 v139, s28, v142
	s_cbranch_scc1 .LBB0_1478
	s_cmp_gt_i32 s8, 2
	s_cbranch_scc0 .LBB0_1479
	s_cmp_eq_u32 s8, 3
	s_mov_b64 s[4:5], -1
	s_cbranch_scc0 .LBB0_1477
	v_lshlrev_b32_e32 v138, 2, v139
	v_lshrrev_b32_e32 v150, 1, v139
	v_and_b32_e32 v138, 16, v138
	v_and_b32_e32 v150, 12, v150
	v_and_b32_e32 v151, 0xffffffe3, v139
	v_or3_b32 v138, v138, v151, v150
	s_mov_b64 s[4:5], 0

; #define LAS __attribute__((address_space(3)))
; __device__ __forceinline__ int map_row_rt(int map, int n) { return map == 0 ? n : (map == 1 ? map_row<1>(n) : (map == 3 ? map_row<3>(n) : map_row<2>(n))); }
; __device__ __forceinline__ void witem_store(const Frame& F, const WItem& t, const f32x4 (&v)[16], LAS unsigned char* tile) {
;     ...
;     for (int pass = 0; pass < 4; ++pass) { const int n = (F.tid >> 4) + 32 * pass, rho = (n & 3) * 32 + (n >> 2);
;         const u32x4 o = *(const LAS u32x4*)(tile + rho * 272 + 16 * c);
;         *(u32x4*)(t.WT + (size_t)map_row_rt(t.map, t.n0 + n) * D + t.k0 + 16 * c) = o; }
; __device__ __forceinline__ void fp8_convert_range(const Frame& F, int l, int start, int stride, int limit) {
;     ...
;         it += 2 * stride;
;         ha = it < limit && witem_decode(F, l, it, ta);
;         if (ha) witem_load(ta, F.wave, F.lane, va);
.LBB0_1488:
	v_ashrrev_i32_e32 v139, 31, v138
	v_lshlrev_b64 v[138:139], 10, v[138:139]
	v_lshl_add_u64 v[138:139], s[0:1], 0, v[138:139]
	v_lshl_add_u64 v[138:139], v[138:139], 0, s[14:15]
	v_lshl_add_u64 v[138:139], v[138:139], 0, v[134:135]
	s_andn2_b64 vcc, exec, s[48:49]
	s_waitcnt lgkmcnt(0)
	global_store_dwordx4 v[138:139], v[130:133], off nt
	s_cbranch_vccnz .LBB0_1494
	v_readlane_b32 s3, v250, 51
	s_add_i32 s56, s56, s3
	s_cmpk_gt_i32 s56, 0xbff
	s_cselect_b64 s[48:49], -1, 0
	s_and_b64 vcc, exec, s[48:49]
	s_cbranch_vccnz .LBB0_1497
	s_cmpk_gt_i32 s56, 0x7ff
	s_mov_b64 s[4:5], -1
	s_cbranch_scc0 .LBB0_1492
	s_add_i32 s0, s56, 0xfffff800
	s_lshr_b32 s0, s0, 5
	s_add_i32 s34, s0, s30
	v_readlane_b32 s60, v249, 8
	s_lshl_b64 s[0:1], s[34:35], 20
	s_lshl_b64 s[4:5], s[34:35], 22
	v_readlane_b32 s66, v249, 14
	v_readlane_b32 s67, v249, 15
	s_add_u32 s50, s66, s4
	s_addc_u32 s51, s67, s5
	s_add_u32 s0, s9, s0
	v_readlane_b32 s61, v249, 9
	v_readlane_b32 s62, v249, 10
	v_readlane_b32 s63, v249, 11
	v_readlane_b32 s64, v249, 12
	v_readlane_b32 s65, v249, 13
	s_addc_u32 s1, s53, s1
	s_and_b32 s3, s56, 31
	s_mov_b64 s[4:5], 0

; #define LAS __attribute__((address_space(3)))
; __device__ __forceinline__ int map_row_rt(int map, int n) { return map == 0 ? n : (map == 1 ? map_row<1>(n) : (map == 3 ? map_row<3>(n) : map_row<2>(n))); }
; __device__ __forceinline__ void witem_store(const Frame& F, const WItem& t, const f32x4 (&v)[16], LAS unsigned char* tile) {
;     ...
;     for (int pass = 0; pass < 4; ++pass) { const int n = (F.tid >> 4) + 32 * pass, rho = (n & 3) * 32 + (n >> 2);
;         const u32x4 o = *(const LAS u32x4*)(tile + rho * 272 + 16 * c);
;         *(u32x4*)(t.WT + (size_t)map_row_rt(t.map, t.n0 + n) * D + t.k0 + 16 * c) = o; }
; __device__ __forceinline__ void fp8_convert_range(const Frame& F, int l, int start, int stride, int limit) {
;     ...
;         witem_store(F, tb, vb, F.lds + 34816);
.LBB0_1512:
	v_ashrrev_i32_e32 v139, 31, v138
	v_lshlrev_b64 v[138:139], 10, v[138:139]
	v_lshl_add_u64 v[138:139], s[42:43], 0, v[138:139]
	s_ashr_i32 s45, s44, 31
	v_lshl_add_u64 v[138:139], v[138:139], 0, s[44:45]
	v_lshl_add_u64 v[138:139], v[138:139], 0, v[134:135]
	s_waitcnt lgkmcnt(0)
	global_store_dwordx4 v[138:139], v[130:133], off nt
	ds_read_b128 v[130:133], v146 offset:34816
	s_cmp_lt_i32 s57, 1
	v_add_u32_e32 v139, s46, v140
	s_cbranch_scc1 .LBB0_1517
	s_cmp_gt_i32 s57, 2
	s_cbranch_scc0 .LBB0_1518
	s_cmp_eq_u32 s57, 3
	s_mov_b64 s[4:5], -1
	s_cbranch_scc0 .LBB0_1516
	v_lshlrev_b32_e32 v138, 2, v139
	v_lshrrev_b32_e32 v150, 1, v139
	v_and_b32_e32 v138, 16, v138
	v_and_b32_e32 v150, 12, v150
	v_and_b32_e32 v151, 0xffffffe3, v139
	v_or3_b32 v138, v138, v151, v150
	s_mov_b64 s[4:5], 0

; #define LAS __attribute__((address_space(3)))
; __device__ __forceinline__ int map_row_rt(int map, int n) { return map == 0 ? n : (map == 1 ? map_row<1>(n) : (map == 3 ? map_row<3>(n) : map_row<2>(n))); }
; __device__ __forceinline__ void witem_store(const Frame& F, const WItem& t, const f32x4 (&v)[16], LAS unsigned char* tile) {
;     ...
;     for (int pass = 0; pass < 4; ++pass) { const int n = (F.tid >> 4) + 32 * pass, rho = (n & 3) * 32 + (n >> 2);
;         const u32x4 o = *(const LAS u32x4*)(tile + rho * 272 + 16 * c);
;         *(u32x4*)(t.WT + (size_t)map_row_rt(t.map, t.n0 + n) * D + t.k0 + 16 * c) = o; }
; __device__ __forceinline__ void fp8_convert_range(const Frame& F, int l, int start, int stride, int limit) {
;     ...
;         witem_store(F, tb, vb, F.lds + 34816);
.LBB0_1527:
	v_ashrrev_i32_e32 v139, 31, v138
	v_lshlrev_b64 v[138:139], 10, v[138:139]
	v_lshl_add_u64 v[138:139], s[42:43], 0, v[138:139]
	v_lshl_add_u64 v[138:139], v[138:139], 0, s[44:45]
	v_lshl_add_u64 v[138:139], v[138:139], 0, v[134:135]
	s_waitcnt lgkmcnt(0)
	global_store_dwordx4 v[138:139], v[130:133], off nt
	ds_read_b128 v[130:133], v147 offset:34816
	s_cmp_lt_i32 s57, 1
	v_add_u32_e32 v139, s46, v141
	s_cbranch_scc1 .LBB0_1532
	s_cmp_gt_i32 s57, 2
	s_cbranch_scc0 .LBB0_1533
	s_cmp_eq_u32 s57, 3
	s_mov_b64 s[4:5], -1
	s_cbranch_scc0 .LBB0_1531
	v_lshlrev_b32_e32 v138, 2, v139
	v_lshrrev_b32_e32 v150, 1, v139
	v_and_b32_e32 v138, 16, v138
	v_and_b32_e32 v150, 12, v150
	v_and_b32_e32 v151, 0xffffffe3, v139
	v_or3_b32 v138, v138, v151, v150
	s_mov_b64 s[4:5], 0

; #define LAS __attribute__((address_space(3)))
; __device__ __forceinline__ int map_row_rt(int map, int n) { return map == 0 ? n : (map == 1 ? map_row<1>(n) : (map == 3 ? map_row<3>(n) : map_row<2>(n))); }
; __device__ __forceinline__ void witem_store(const Frame& F, const WItem& t, const f32x4 (&v)[16], LAS unsigned char* tile) {
;     ...
;     for (int pass = 0; pass < 4; ++pass) { const int n = (F.tid >> 4) + 32 * pass, rho = (n & 3) * 32 + (n >> 2);
;         const u32x4 o = *(const LAS u32x4*)(tile + rho * 272 + 16 * c);
;         *(u32x4*)(t.WT + (size_t)map_row_rt(t.map, t.n0 + n) * D + t.k0 + 16 * c) = o; }
; __device__ __forceinline__ void fp8_convert_range(const Frame& F, int l, int start, int stride, int limit) {
;     ...
;         witem_store(F, tb, vb, F.lds + 34816);
.LBB0_1542:
	v_ashrrev_i32_e32 v139, 31, v138
	v_lshlrev_b64 v[138:139], 10, v[138:139]
	v_lshl_add_u64 v[138:139], s[42:43], 0, v[138:139]
	v_lshl_add_u64 v[138:139], v[138:139], 0, s[44:45]
	v_lshl_add_u64 v[138:139], v[138:139], 0, v[134:135]
	s_waitcnt lgkmcnt(0)
	global_store_dwordx4 v[138:139], v[130:133], off nt
	ds_read_b128 v[130:133], v148 offset:34816
	s_cmp_lt_i32 s57, 1
	v_add_u32_e32 v139, s46, v142
	s_cbranch_scc1 .LBB0_1547
	s_cmp_gt_i32 s57, 2
	s_cbranch_scc0 .LBB0_1548
	s_cmp_eq_u32 s57, 3
	s_mov_b64 s[4:5], -1
	s_cbranch_scc0 .LBB0_1546
	v_lshlrev_b32_e32 v138, 2, v139
	v_lshrrev_b32_e32 v150, 1, v139
	v_and_b32_e32 v138, 16, v138
	v_and_b32_e32 v150, 12, v150
	v_and_b32_e32 v151, 0xffffffe3, v139
	v_or3_b32 v138, v138, v151, v150
	s_mov_b64 s[4:5], 0

; #define LAS __attribute__((address_space(3)))
; __device__ __forceinline__ int map_row_rt(int map, int n) { return map == 0 ? n : (map == 1 ? map_row<1>(n) : (map == 3 ? map_row<3>(n) : map_row<2>(n))); }
; __device__ __forceinline__ void witem_store(const Frame& F, const WItem& t, const f32x4 (&v)[16], LAS unsigned char* tile) {
;     ...
;     for (int pass = 0; pass < 4; ++pass) { const int n = (F.tid >> 4) + 32 * pass, rho = (n & 3) * 32 + (n >> 2);
;         const u32x4 o = *(const LAS u32x4*)(tile + rho * 272 + 16 * c);
;         *(u32x4*)(t.WT + (size_t)map_row_rt(t.map, t.n0 + n) * D + t.k0 + 16 * c) = o; }
.LBB0_1606:
	v_ashrrev_i32_e32 v139, 31, v138
	v_lshlrev_b64 v[138:139], 10, v[138:139]
	v_lshl_add_u64 v[138:139], s[44:45], 0, v[138:139]
	v_lshl_add_u64 v[138:139], v[138:139], 0, s[46:47]
	v_lshl_add_u64 v[138:139], v[138:139], 0, v[134:135]
	s_waitcnt lgkmcnt(0)
	global_store_dwordx4 v[138:139], v[130:133], off nt
	s_and_b64 vcc, exec, s[50:51]
	s_cbranch_vccnz .LBB0_1742

; #define LAS __attribute__((address_space(3)))
; __device__ __forceinline__ int map_row_rt(int map, int n) { return map == 0 ? n : (map == 1 ? map_row<1>(n) : (map == 3 ? map_row<3>(n) : map_row<2>(n))); }
; __device__ __forceinline__ void witem_store(const Frame& F, const WItem& t, const f32x4 (&v)[16], LAS unsigned char* tile) {
;     ...
;     for (int pass = 0; pass < 4; ++pass) { const int n = (F.tid >> 4) + 32 * pass, rho = (n & 3) * 32 + (n >> 2);
;         const u32x4 o = *(const LAS u32x4*)(tile + rho * 272 + 16 * c);
;         *(u32x4*)(t.WT + (size_t)map_row_rt(t.map, t.n0 + n) * D + t.k0 + 16 * c) = o; }
.LBB0_1629:
	v_ashrrev_i32_e32 v139, 31, v138
	v_lshlrev_b64 v[138:139], 10, v[138:139]
	v_lshl_add_u64 v[138:139], s[14:15], 0, v[138:139]
	s_ashr_i32 s29, s28, 31
	v_lshl_add_u64 v[138:139], v[138:139], 0, s[28:29]
	v_lshl_add_u64 v[138:139], v[138:139], 0, v[134:135]
	s_waitcnt lgkmcnt(0)
	global_store_dwordx4 v[138:139], v[130:133], off nt
	ds_read_b128 v[130:133], v146
	s_movk_i32 s3, 0xc00
	s_cmp_lt_i32 s8, 1
	v_add_u32_e32 v139, s36, v140
	s_cbranch_scc1 .LBB0_1634
	s_cmp_gt_i32 s8, 2
	s_cbranch_scc0 .LBB0_1635
	s_cmp_eq_u32 s8, 3
	s_mov_b64 s[4:5], -1
	s_cbranch_scc0 .LBB0_1633
	v_lshlrev_b32_e32 v138, 2, v139
	v_lshrrev_b32_e32 v150, 1, v139
	v_and_b32_e32 v138, 16, v138
	v_and_b32_e32 v150, 12, v150
	v_and_b32_e32 v151, 0xffffffe3, v139
	v_or3_b32 v138, v138, v151, v150
	s_mov_b64 s[4:5], 0

; #define LAS __attribute__((address_space(3)))
; __device__ __forceinline__ int map_row_rt(int map, int n) { return map == 0 ? n : (map == 1 ? map_row<1>(n) : (map == 3 ? map_row<3>(n) : map_row<2>(n))); }
; __device__ __forceinline__ void witem_store(const Frame& F, const WItem& t, const f32x4 (&v)[16], LAS unsigned char* tile) {
;     ...
;     for (int pass = 0; pass < 4; ++pass) { const int n = (F.tid >> 4) + 32 * pass, rho = (n & 3) * 32 + (n >> 2);
;         const u32x4 o = *(const LAS u32x4*)(tile + rho * 272 + 16 * c);
;         *(u32x4*)(t.WT + (size_t)map_row_rt(t.map, t.n0 + n) * D + t.k0 + 16 * c) = o; }
.LBB0_1644:
	v_ashrrev_i32_e32 v139, 31, v138
	v_lshlrev_b64 v[138:139], 10, v[138:139]
	v_lshl_add_u64 v[138:139], s[14:15], 0, v[138:139]
	v_lshl_add_u64 v[138:139], v[138:139], 0, s[28:29]
	v_lshl_add_u64 v[138:139], v[138:139], 0, v[134:135]
	s_waitcnt lgkmcnt(0)
	global_store_dwordx4 v[138:139], v[130:133], off nt
	ds_read_b128 v[130:133], v147
	s_cmp_lt_i32 s8, 1
	v_add_u32_e32 v139, s36, v141
	s_cbranch_scc1 .LBB0_1649
	s_cmp_gt_i32 s8, 2
	s_cbranch_scc0 .LBB0_1650
	s_cmp_eq_u32 s8, 3
	s_mov_b64 s[4:5], -1
	s_cbranch_scc0 .LBB0_1648
	v_lshlrev_b32_e32 v138, 2, v139
	v_lshrrev_b32_e32 v150, 1, v139
	v_and_b32_e32 v138, 16, v138
	v_and_b32_e32 v150, 12, v150
	v_and_b32_e32 v151, 0xffffffe3, v139
	v_or3_b32 v138, v138, v151, v150
	s_mov_b64 s[4:5], 0

; #define LAS __attribute__((address_space(3)))
; __device__ __forceinline__ int map_row_rt(int map, int n) { return map == 0 ? n : (map == 1 ? map_row<1>(n) : (map == 3 ? map_row<3>(n) : map_row<2>(n))); }
; __device__ __forceinline__ void witem_store(const Frame& F, const WItem& t, const f32x4 (&v)[16], LAS unsigned char* tile) {
;     ...
;     for (int pass = 0; pass < 4; ++pass) { const int n = (F.tid >> 4) + 32 * pass, rho = (n & 3) * 32 + (n >> 2);
;         const u32x4 o = *(const LAS u32x4*)(tile + rho * 272 + 16 * c);
;         *(u32x4*)(t.WT + (size_t)map_row_rt(t.map, t.n0 + n) * D + t.k0 + 16 * c) = o; }
.LBB0_1659:
	v_ashrrev_i32_e32 v139, 31, v138
	v_lshlrev_b64 v[138:139], 10, v[138:139]
	v_lshl_add_u64 v[138:139], s[14:15], 0, v[138:139]
	v_lshl_add_u64 v[138:139], v[138:139], 0, s[28:29]
	v_lshl_add_u64 v[138:139], v[138:139], 0, v[134:135]
	s_waitcnt lgkmcnt(0)
	global_store_dwordx4 v[138:139], v[130:133], off nt
	ds_read_b128 v[130:133], v148
	s_cmp_lt_i32 s8, 1
	v_add_u32_e32 v139, s36, v142
	s_cbranch_scc1 .LBB0_1664
	s_cmp_gt_i32 s8, 2
	s_cbranch_scc0 .LBB0_1665
	s_cmp_eq_u32 s8, 3
	s_mov_b64 s[4:5], -1
	s_cbranch_scc0 .LBB0_1663
	v_lshlrev_b32_e32 v138, 2, v139
	v_lshrrev_b32_e32 v150, 1, v139
	v_and_b32_e32 v138, 16, v138
	v_and_b32_e32 v150, 12, v150
	v_and_b32_e32 v151, 0xffffffe3, v139
	v_or3_b32 v138, v138, v151, v150
	s_mov_b64 s[4:5], 0

; #define LAS __attribute__((address_space(3)))
; __device__ __forceinline__ int map_row_rt(int map, int n) { return map == 0 ? n : (map == 1 ? map_row<1>(n) : (map == 3 ? map_row<3>(n) : map_row<2>(n))); }
; __device__ __forceinline__ void witem_store(const Frame& F, const WItem& t, const f32x4 (&v)[16], LAS unsigned char* tile) {
;     ...
;     for (int pass = 0; pass < 4; ++pass) { const int n = (F.tid >> 4) + 32 * pass, rho = (n & 3) * 32 + (n >> 2);
;         const u32x4 o = *(const LAS u32x4*)(tile + rho * 272 + 16 * c);
;         *(u32x4*)(t.WT + (size_t)map_row_rt(t.map, t.n0 + n) * D + t.k0 + 16 * c) = o; }
; __device__ __forceinline__ void fp8_convert_range(const Frame& F, int l, int start, int stride, int limit) {
;     ...
;         it += 2 * stride;
;         ha = it < limit && witem_decode(F, l, it, ta);
;         if (ha) witem_load(ta, F.wave, F.lane, va);
.LBB0_1674:
	v_ashrrev_i32_e32 v139, 31, v138
	v_lshlrev_b64 v[138:139], 10, v[138:139]
	v_lshl_add_u64 v[138:139], s[14:15], 0, v[138:139]
	v_lshl_add_u64 v[138:139], v[138:139], 0, s[28:29]
	v_lshl_add_u64 v[138:139], v[138:139], 0, v[134:135]
	s_andn2_b64 vcc, exec, s[50:51]
	s_waitcnt lgkmcnt(0)
	global_store_dwordx4 v[138:139], v[130:133], off nt
	s_cbranch_vccnz .LBB0_1680
	v_readlane_b32 s3, v250, 51
	s_add_i32 s57, s57, s3
	s_cmpk_gt_i32 s57, 0xbff
	s_cselect_b64 s[50:51], -1, 0
	s_and_b64 vcc, exec, s[50:51]
	s_movk_i32 s29, 0xc00
	s_cbranch_vccnz .LBB0_1683
	s_cmpk_gt_i32 s57, 0x7ff
	s_mov_b64 s[4:5], -1
	s_cbranch_scc0 .LBB0_1678
	s_add_i32 s3, s57, 0xfffff800
	s_lshr_b32 s3, s3, 5
	s_add_i32 s34, s3, s30
	v_readlane_b32 s60, v249, 8
	s_lshl_b64 s[4:5], s[34:35], 20
	s_lshl_b64 s[6:7], s[34:35], 22
	v_readlane_b32 s66, v249, 14
	v_readlane_b32 s67, v249, 15
	s_add_u32 s52, s66, s6
	s_addc_u32 s53, s67, s7
	s_add_u32 s14, s9, s4
	v_readlane_b32 s61, v249, 9
	v_readlane_b32 s62, v249, 10
	v_readlane_b32 s63, v249, 11
	v_readlane_b32 s64, v249, 12
	v_readlane_b32 s65, v249, 13
	s_addc_u32 s15, s54, s5
	s_and_b32 s3, s57, 31
	s_mov_b64 s[4:5], 0

; #define LAS __attribute__((address_space(3)))
; __device__ __forceinline__ int map_row_rt(int map, int n) { return map == 0 ? n : (map == 1 ? map_row<1>(n) : (map == 3 ? map_row<3>(n) : map_row<2>(n))); }
; __device__ __forceinline__ void witem_store(const Frame& F, const WItem& t, const f32x4 (&v)[16], LAS unsigned char* tile) {
;     ...
;     for (int pass = 0; pass < 4; ++pass) { const int n = (F.tid >> 4) + 32 * pass, rho = (n & 3) * 32 + (n >> 2);
;         const u32x4 o = *(const LAS u32x4*)(tile + rho * 272 + 16 * c);
;         *(u32x4*)(t.WT + (size_t)map_row_rt(t.map, t.n0 + n) * D + t.k0 + 16 * c) = o; }
; __device__ __forceinline__ void fp8_convert_range(const Frame& F, int l, int start, int stride, int limit) {
;     ...
;         witem_store(F, tb, vb, F.lds + 34816);
.LBB0_1698:
	v_ashrrev_i32_e32 v139, 31, v138
	v_lshlrev_b64 v[138:139], 10, v[138:139]
	v_lshl_add_u64 v[138:139], s[44:45], 0, v[138:139]
	s_ashr_i32 s47, s46, 31
	v_lshl_add_u64 v[138:139], v[138:139], 0, s[46:47]
	v_lshl_add_u64 v[138:139], v[138:139], 0, v[134:135]
	s_waitcnt lgkmcnt(0)
	global_store_dwordx4 v[138:139], v[130:133], off nt
	ds_read_b128 v[130:133], v146 offset:34816
	s_cmp_lt_i32 s58, 1
	v_add_u32_e32 v139, s48, v140
	s_cbranch_scc1 .LBB0_1703
	s_cmp_gt_i32 s58, 2
	s_cbranch_scc0 .LBB0_1704
	s_cmp_eq_u32 s58, 3
	s_mov_b64 s[4:5], -1
	s_cbranch_scc0 .LBB0_1702
	v_lshlrev_b32_e32 v138, 2, v139
	v_lshrrev_b32_e32 v150, 1, v139
	v_and_b32_e32 v138, 16, v138
	v_and_b32_e32 v150, 12, v150
	v_and_b32_e32 v151, 0xffffffe3, v139
	v_or3_b32 v138, v138, v151, v150
	s_mov_b64 s[4:5], 0

; #define LAS __attribute__((address_space(3)))
; __device__ __forceinline__ int map_row_rt(int map, int n) { return map == 0 ? n : (map == 1 ? map_row<1>(n) : (map == 3 ? map_row<3>(n) : map_row<2>(n))); }
; __device__ __forceinline__ void witem_store(const Frame& F, const WItem& t, const f32x4 (&v)[16], LAS unsigned char* tile) {
;     ...
;     for (int pass = 0; pass < 4; ++pass) { const int n = (F.tid >> 4) + 32 * pass, rho = (n & 3) * 32 + (n >> 2);
;         const u32x4 o = *(const LAS u32x4*)(tile + rho * 272 + 16 * c);
;         *(u32x4*)(t.WT + (size_t)map_row_rt(t.map, t.n0 + n) * D + t.k0 + 16 * c) = o; }
; __device__ __forceinline__ void fp8_convert_range(const Frame& F, int l, int start, int stride, int limit) {
;     ...
;         witem_store(F, tb, vb, F.lds + 34816);
.LBB0_1713:
	v_ashrrev_i32_e32 v139, 31, v138
	v_lshlrev_b64 v[138:139], 10, v[138:139]
	v_lshl_add_u64 v[138:139], s[44:45], 0, v[138:139]
	v_lshl_add_u64 v[138:139], v[138:139], 0, s[46:47]
	v_lshl_add_u64 v[138:139], v[138:139], 0, v[134:135]
	s_waitcnt lgkmcnt(0)
	global_store_dwordx4 v[138:139], v[130:133], off nt
	ds_read_b128 v[130:133], v147 offset:34816
	s_cmp_lt_i32 s58, 1
	v_add_u32_e32 v139, s48, v141
	s_cbranch_scc1 .LBB0_1718
	s_cmp_gt_i32 s58, 2
	s_cbranch_scc0 .LBB0_1719
	s_cmp_eq_u32 s58, 3
	s_mov_b64 s[4:5], -1
	s_cbranch_scc0 .LBB0_1717
	v_lshlrev_b32_e32 v138, 2, v139
	v_lshrrev_b32_e32 v150, 1, v139
	v_and_b32_e32 v138, 16, v138
	v_and_b32_e32 v150, 12, v150
	v_and_b32_e32 v151, 0xffffffe3, v139
	v_or3_b32 v138, v138, v151, v150
	s_mov_b64 s[4:5], 0

; #define LAS __attribute__((address_space(3)))
; __device__ __forceinline__ int map_row_rt(int map, int n) { return map == 0 ? n : (map == 1 ? map_row<1>(n) : (map == 3 ? map_row<3>(n) : map_row<2>(n))); }
; __device__ __forceinline__ void witem_store(const Frame& F, const WItem& t, const f32x4 (&v)[16], LAS unsigned char* tile) {
;     ...
;     for (int pass = 0; pass < 4; ++pass) { const int n = (F.tid >> 4) + 32 * pass, rho = (n & 3) * 32 + (n >> 2);
;         const u32x4 o = *(const LAS u32x4*)(tile + rho * 272 + 16 * c);
;         *(u32x4*)(t.WT + (size_t)map_row_rt(t.map, t.n0 + n) * D + t.k0 + 16 * c) = o; }
; __device__ __forceinline__ void fp8_convert_range(const Frame& F, int l, int start, int stride, int limit) {
;     ...
;         witem_store(F, tb, vb, F.lds + 34816);
.LBB0_1728:
	v_ashrrev_i32_e32 v139, 31, v138
	v_lshlrev_b64 v[138:139], 10, v[138:139]
	v_lshl_add_u64 v[138:139], s[44:45], 0, v[138:139]
	v_lshl_add_u64 v[138:139], v[138:139], 0, s[46:47]
	v_lshl_add_u64 v[138:139], v[138:139], 0, v[134:135]
	s_waitcnt lgkmcnt(0)
	global_store_dwordx4 v[138:139], v[130:133], off nt
	ds_read_b128 v[130:133], v148 offset:34816
	s_cmp_lt_i32 s58, 1
	v_add_u32_e32 v139, s48, v142
	s_cbranch_scc1 .LBB0_1733
	s_cmp_gt_i32 s58, 2
	s_cbranch_scc0 .LBB0_1734
	s_cmp_eq_u32 s58, 3
	s_mov_b64 s[4:5], -1
	s_cbranch_scc0 .LBB0_1732
	v_lshlrev_b32_e32 v138, 2, v139
	v_lshrrev_b32_e32 v150, 1, v139
	v_and_b32_e32 v138, 16, v138
	v_and_b32_e32 v150, 12, v150
	v_and_b32_e32 v151, 0xffffffe3, v139
	v_or3_b32 v138, v138, v151, v150
	s_mov_b64 s[4:5], 0

; #define LAS __attribute__((address_space(3)))
; __device__ __forceinline__ int map_row_rt(int map, int n) { return map == 0 ? n : (map == 1 ? map_row<1>(n) : (map == 3 ? map_row<3>(n) : map_row<2>(n))); }
; __device__ __forceinline__ void witem_store(const Frame& F, const WItem& t, const f32x4 (&v)[16], LAS unsigned char* tile) {
;     ...
;     for (int pass = 0; pass < 4; ++pass) { const int n = (F.tid >> 4) + 32 * pass, rho = (n & 3) * 32 + (n >> 2);
;         const u32x4 o = *(const LAS u32x4*)(tile + rho * 272 + 16 * c);
;         *(u32x4*)(t.WT + (size_t)map_row_rt(t.map, t.n0 + n) * D + t.k0 + 16 * c) = o; }
; __device__ __forceinline__ void fp8_convert_range(const Frame& F, int l, int start, int stride, int limit) {
;     ...
;         it += 2 * stride;
;         ha = it < limit && witem_decode(F, l, it, ta);
;         if (ha) witem_load(ta, F.wave, F.lane, va);
.LBB0_1930:
	v_ashrrev_i32_e32 v139, 31, v138
	v_lshlrev_b64 v[138:139], 10, v[138:139]
	v_lshl_add_u64 v[138:139], s[0:1], 0, v[138:139]
	v_lshl_add_u64 v[138:139], v[138:139], 0, s[14:15]
	v_lshl_add_u64 v[138:139], v[138:139], 0, v[134:135]
	s_andn2_b64 vcc, exec, s[48:49]
	s_waitcnt lgkmcnt(0)
	global_store_dwordx4 v[138:139], v[130:133], off nt
	s_cbranch_vccnz .LBB0_1936
	v_readlane_b32 s3, v250, 51
	s_add_i32 s54, s54, s3
	s_cmpk_gt_i32 s54, 0xbff
	s_cselect_b64 s[48:49], -1, 0
	s_and_b64 vcc, exec, s[48:49]
	s_cbranch_vccnz .LBB0_1939
	s_cmpk_gt_i32 s54, 0x7ff
	s_mov_b64 s[4:5], -1
	s_cbranch_scc0 .LBB0_1934
	s_add_i32 s0, s54, 0xfffff800
	s_lshr_b32 s0, s0, 5
	s_add_i32 s34, s0, s30
	v_readlane_b32 s56, v249, 8
	s_lshl_b64 s[0:1], s[34:35], 20
	s_lshl_b64 s[4:5], s[34:35], 22
	v_readlane_b32 s62, v249, 14
	v_readlane_b32 s63, v249, 15
	s_add_u32 s50, s62, s4
	s_addc_u32 s51, s63, s5
	s_add_u32 s0, s9, s0
	v_readlane_b32 s57, v249, 9
	v_readlane_b32 s58, v249, 10
	v_readlane_b32 s59, v249, 11
	v_readlane_b32 s60, v249, 12
	v_readlane_b32 s61, v249, 13
	s_addc_u32 s1, s11, s1
	s_and_b32 s3, s54, 31
	s_mov_b64 s[4:5], 0

; #define LAS __attribute__((address_space(3)))
; __device__ __forceinline__ int map_row_rt(int map, int n) { return map == 0 ? n : (map == 1 ? map_row<1>(n) : (map == 3 ? map_row<3>(n) : map_row<2>(n))); }
; __device__ __forceinline__ void witem_store(const Frame& F, const WItem& t, const f32x4 (&v)[16], LAS unsigned char* tile) {
;     ...
;     for (int pass = 0; pass < 4; ++pass) { const int n = (F.tid >> 4) + 32 * pass, rho = (n & 3) * 32 + (n >> 2);
;         const u32x4 o = *(const LAS u32x4*)(tile + rho * 272 + 16 * c);
;         *(u32x4*)(t.WT + (size_t)map_row_rt(t.map, t.n0 + n) * D + t.k0 + 16 * c) = o; }
; __device__ __forceinline__ void fp8_convert_range(const Frame& F, int l, int start, int stride, int limit) {
;     ...
;         witem_store(F, tb, vb, F.lds + 34816);
.LBB0_1954:
	v_ashrrev_i32_e32 v139, 31, v138
	v_lshlrev_b64 v[138:139], 10, v[138:139]
	v_lshl_add_u64 v[138:139], s[42:43], 0, v[138:139]
	s_ashr_i32 s45, s44, 31
	v_lshl_add_u64 v[138:139], v[138:139], 0, s[44:45]
	v_lshl_add_u64 v[138:139], v[138:139], 0, v[134:135]
	s_waitcnt lgkmcnt(0)
	global_store_dwordx4 v[138:139], v[130:133], off nt
	ds_read_b128 v[130:133], v146 offset:34816
	s_cmp_lt_i32 s55, 1
	v_add_u32_e32 v139, s46, v140
	s_cbranch_scc1 .LBB0_1959
	s_cmp_gt_i32 s55, 2
	s_cbranch_scc0 .LBB0_1960
	s_cmp_eq_u32 s55, 3
	s_mov_b64 s[4:5], -1
	s_cbranch_scc0 .LBB0_1958
	v_lshlrev_b32_e32 v138, 2, v139
	v_lshrrev_b32_e32 v150, 1, v139
	v_and_b32_e32 v138, 16, v138
	v_and_b32_e32 v150, 12, v150
	v_and_b32_e32 v151, 0xffffffe3, v139
	v_or3_b32 v138, v138, v151, v150
	s_mov_b64 s[4:5], 0

; #define LAS __attribute__((address_space(3)))
; __device__ __forceinline__ int map_row_rt(int map, int n) { return map == 0 ? n : (map == 1 ? map_row<1>(n) : (map == 3 ? map_row<3>(n) : map_row<2>(n))); }
; __device__ __forceinline__ void witem_store(const Frame& F, const WItem& t, const f32x4 (&v)[16], LAS unsigned char* tile) {
;     ...
;     for (int pass = 0; pass < 4; ++pass) { const int n = (F.tid >> 4) + 32 * pass, rho = (n & 3) * 32 + (n >> 2);
;         const u32x4 o = *(const LAS u32x4*)(tile + rho * 272 + 16 * c);
;         *(u32x4*)(t.WT + (size_t)map_row_rt(t.map, t.n0 + n) * D + t.k0 + 16 * c) = o; }
; __device__ __forceinline__ void fp8_convert_range(const Frame& F, int l, int start, int stride, int limit) {
;     ...
;         witem_store(F, tb, vb, F.lds + 34816);
.LBB0_1969:
	v_ashrrev_i32_e32 v139, 31, v138
	v_lshlrev_b64 v[138:139], 10, v[138:139]
	v_lshl_add_u64 v[138:139], s[42:43], 0, v[138:139]
	v_lshl_add_u64 v[138:139], v[138:139], 0, s[44:45]
	v_lshl_add_u64 v[138:139], v[138:139], 0, v[134:135]
	s_waitcnt lgkmcnt(0)
	global_store_dwordx4 v[138:139], v[130:133], off nt
	ds_read_b128 v[130:133], v147 offset:34816
	s_cmp_lt_i32 s55, 1
	v_add_u32_e32 v139, s46, v141
	s_cbranch_scc1 .LBB0_1974
	s_cmp_gt_i32 s55, 2
	s_cbranch_scc0 .LBB0_1975
	s_cmp_eq_u32 s55, 3
	s_mov_b64 s[4:5], -1
	s_cbranch_scc0 .LBB0_1973
	v_lshlrev_b32_e32 v138, 2, v139
	v_lshrrev_b32_e32 v150, 1, v139
	v_and_b32_e32 v138, 16, v138
	v_and_b32_e32 v150, 12, v150
	v_and_b32_e32 v151, 0xffffffe3, v139
	v_or3_b32 v138, v138, v151, v150
	s_mov_b64 s[4:5], 0

; #define LAS __attribute__((address_space(3)))
; __device__ __forceinline__ int map_row_rt(int map, int n) { return map == 0 ? n : (map == 1 ? map_row<1>(n) : (map == 3 ? map_row<3>(n) : map_row<2>(n))); }
; __device__ __forceinline__ void witem_store(const Frame& F, const WItem& t, const f32x4 (&v)[16], LAS unsigned char* tile) {
;     ...
;     for (int pass = 0; pass < 4; ++pass) { const int n = (F.tid >> 4) + 32 * pass, rho = (n & 3) * 32 + (n >> 2);
;         const u32x4 o = *(const LAS u32x4*)(tile + rho * 272 + 16 * c);
;         *(u32x4*)(t.WT + (size_t)map_row_rt(t.map, t.n0 + n) * D + t.k0 + 16 * c) = o; }
; __device__ __forceinline__ void fp8_convert_range(const Frame& F, int l, int start, int stride, int limit) {
;     ...
;         witem_store(F, tb, vb, F.lds + 34816);
.LBB0_1984:
	v_ashrrev_i32_e32 v139, 31, v138
	v_lshlrev_b64 v[138:139], 10, v[138:139]
	v_lshl_add_u64 v[138:139], s[42:43], 0, v[138:139]
	v_lshl_add_u64 v[138:139], v[138:139], 0, s[44:45]
	v_lshl_add_u64 v[138:139], v[138:139], 0, v[134:135]
	s_waitcnt lgkmcnt(0)
	global_store_dwordx4 v[138:139], v[130:133], off nt
	ds_read_b128 v[130:133], v148 offset:34816
	s_cmp_lt_i32 s55, 1
	v_add_u32_e32 v139, s46, v142
	s_cbranch_scc1 .LBB0_1989
	s_cmp_gt_i32 s55, 2
	s_cbranch_scc0 .LBB0_1990
	s_cmp_eq_u32 s55, 3
	s_mov_b64 s[4:5], -1
	s_cbranch_scc0 .LBB0_1988
	v_lshlrev_b32_e32 v138, 2, v139
	v_lshrrev_b32_e32 v150, 1, v139
	v_and_b32_e32 v138, 16, v138
	v_and_b32_e32 v150, 12, v150
	v_and_b32_e32 v151, 0xffffffe3, v139
	v_or3_b32 v138, v138, v151, v150
	s_mov_b64 s[4:5], 0
